# diff-attention loop: next-tile staging (LDS writes, address math, global loads) issued inside the MFMA stream instead of after it, tile index clamped so it is unconditional
# baseline (speedup 1.0000x reference)
;     ...
;     for (int i = 0; i < nt; ++i) {
;         const int j = jn;
;         const bool more = (i + 1 < nt);
;         if (more) { jn = next(j); if (probe != 1) kv_gload<DV, HAS_V>(st, Kb, VTb, ldv, jn * 64); }
;         if (probe != 2) body(j, (const unsigned char*)(lds + (i & 1) * SB));
;         if (more && probe != 1) kv_sstore<DV, HAS_V>(st, lds + ((i + 1) & 1) * SB);
;         __syncthreads();
;     }
;     ...
;         kv_loop<128, true>(lds, Kb, VTb, 4096, ntl, 0, [](int j) { return j + 1; }, [&](int j, const unsigned char* sb) {
;             const int k0 = j * 64;
;             if (k0 <= wq0 + 31) {
;                 f32x16 s0, s1; attn_scores(sb, qf, r, h, s0, s1);
;                 if (k0 + 63 > wq0) {
.Ldl_xdone:
	s_waitcnt lgkmcnt(0)
	s_barrier
	s_setprio 3
	s_cmp_le_i32 s64, s60
	s_cbranch_scc0 .Ldl_stage
	v_add3_u32 v199, s61, v168, v191
	s_add_i32 s65, s24, 1
	s_cmp_ge_u32 s65, s58
	s_cbranch_scc1 .Ldl_pvonly
	s_lshl_b32 s66, s65, 6
	s_cmp_le_i32 s66, s60
	s_cbranch_scc0 .Ldl_pvonly
	v_add3_u32 v7, s62, v191, v168

; #define MFMA(a, b, c) __builtin_amdgcn_mfma_f32_32x32x16_bf16((a), (b), (c), 0, 0, 0)
; template <int DV, bool HAS_V>
; DI void kv_sstore(const KVStage<DV>& st, unsigned char* buf) {
;     const int tid = threadIdx.x;
;     *(u32x4*)(buf + (tid >> 3) * KP + (tid & 7) * 16) = st.k[0];
;     if (HAS_V) {
; #pragma unroll
;         for (int i = 0; i < DV / 64; ++i) {
;             const int c = tid + 512 * i, kc = c & 7; unsigned char* q = buf + KT_BYTES + (c >> 3) * VP + (kc >> 1) * 32 + (kc & 1) * 8;
;             u32x2 lo, hi; lo.x = st.v[i].x; lo.y = st.v[i].y; hi.x = st.v[i].z; hi.y = st.v[i].w;
;             *(u32x2*)q = lo; *(u32x2*)(q + 16) = hi;
;         }
;     }
; }
; template <int DV>
; DI void attn_pv(const unsigned char* vb, const bf16x8 (&pf)[2][2], int r, int h, f32x16 (&o)[DV / 32]) {
; #pragma unroll
;     for (int dt = 0; dt < DV / 32; ++dt)
; #pragma unroll
;         for (int mt = 0; mt < 2; ++mt)
; #pragma unroll
;             for (int sp = 0; sp < 2; ++sp) {
;                 const bf16x8 vf = *(const bf16x8*)(vb + (dt * 32 + r) * VP + (2 * mt + sp) * 32 + h * 16);
;                 o[dt] = MFMA(vf, pf[mt][sp], o[dt]);
;             }
; }
	ds_read_b128 v[214:217], v199 offset:9216
	ds_read_b128 v[218:221], v199 offset:9248
	ds_read_b128 v[222:225], v199 offset:9280
	ds_read_b128 v[226:229], v199 offset:9312
	ds_read_b128 v[230:233], v199 offset:13824
	ds_read_b128 v[234:237], v199 offset:13856
	s_waitcnt lgkmcnt(5)
	v_mfma_f32_32x32x16_bf16 v[66:81], v[214:217], v[200:203], v[66:81]
	ds_read_b128 v[214:217], v199 offset:13888
	s_waitcnt vmcnt(0)
	v_add3_u32 v10, s63, v159, v195
	s_waitcnt lgkmcnt(5)
	v_mfma_f32_32x32x16_bf16 v[66:81], v[218:221], v[204:207], v[66:81]
	ds_read_b128 v[218:221], v199 offset:13920
	ds_write_b128 v10, v[146:149]
	v_add3_u32 v10, s63, v196, v197
	s_waitcnt lgkmcnt(5)
	v_mfma_f32_32x32x16_bf16 v[66:81], v[222:225], v[208:211], v[66:81]
	ds_read_b128 v[222:225], v199 offset:18432
	v_add_u32_e32 v11, v10, v159
	v_add_u32_e32 v10, v10, v180
	s_waitcnt lgkmcnt(5)
	v_mfma_f32_32x32x16_bf16 v[66:81], v[226:229], v[12:15], v[66:81]
	ds_read_b128 v[226:229], v199 offset:18464
	v_add_u32_e32 v11, 0x2000, v11
	v_add_u32_e32 v10, 0x2000, v10
	s_waitcnt lgkmcnt(5)
	v_mfma_f32_32x32x16_bf16 v[50:65], v[230:233], v[200:203], v[50:65]
	ds_read_b128 v[230:233], v199 offset:18496
	ds_write2_b64 v11, v[150:151], v[152:153] offset0:128 offset1:130
	ds_write2_b64 v10, v[154:155], v[156:157] offset0:128 offset1:130
	s_waitcnt lgkmcnt(5)
	v_mfma_f32_32x32x16_bf16 v[50:65], v[234:237], v[204:207], v[50:65]
	ds_read_b128 v[234:237], v199 offset:18528

; #define MFMA(a, b, c) __builtin_amdgcn_mfma_f32_32x32x16_bf16((a), (b), (c), 0, 0, 0)
; template <int DV, bool HAS_V>
; DI void kv_gload(KVStage<DV>& st, const bf16_t* __restrict__ Kb, const bf16_t* __restrict__ VTb, int ldv, int key0) {
;     const int tid = threadIdx.x;
;     st.k[0] = *(const u32x4*)(Kb + (size_t)(key0 + (tid >> 3)) * 64 + (tid & 7) * 8);
;     if (HAS_V) {
; #pragma unroll
;         for (int i = 0; i < DV / 64; ++i) { const int c = tid + 512 * i; st.v[i] = *(const u32x4*)(VTb + (size_t)(key0 >> 6) * (DV * 64) + c * 8); }
;     }
; }
; template <int DV>
; DI void attn_pv(const unsigned char* vb, const bf16x8 (&pf)[2][2], int r, int h, f32x16 (&o)[DV / 32]) {
; #pragma unroll
;     for (int dt = 0; dt < DV / 32; ++dt)
; #pragma unroll
;         for (int mt = 0; mt < 2; ++mt)
; #pragma unroll
;             for (int sp = 0; sp < 2; ++sp) {
;                 const bf16x8 vf = *(const bf16x8*)(vb + (dt * 32 + r) * VP + (2 * mt + sp) * 32 + h * 16);
;                 o[dt] = MFMA(vf, pf[mt][sp], o[dt]);
;             }
; }
	s_add_i32 s65, s24, 3
	s_waitcnt lgkmcnt(5)
	v_mfma_f32_32x32x16_bf16 v[50:65], v[214:217], v[208:211], v[50:65]
	ds_read_b128 v[214:217], v199 offset:23040
	s_add_i32 s66, s58, -1
	s_min_u32 s65, s65, s66
	s_waitcnt lgkmcnt(5)
	v_mfma_f32_32x32x16_bf16 v[50:65], v[218:221], v[12:15], v[50:65]
	ds_read_b128 v[218:221], v199 offset:23072
	s_lshl_b32 s66, s65, 6
	v_add_u32_e32 v8, s66, v187
	s_waitcnt lgkmcnt(5)
	v_mfma_f32_32x32x16_bf16 v[34:49], v[222:225], v[200:203], v[34:49]
	ds_read_b128 v[222:225], v199 offset:23104
	v_mov_b32_e32 v9, v3
	v_lshlrev_b64 v[8:9], 7, v[8:9]
	s_waitcnt lgkmcnt(5)
	v_mfma_f32_32x32x16_bf16 v[34:49], v[226:229], v[204:207], v[34:49]
	ds_read_b128 v[226:229], v199 offset:23136
	v_lshl_add_u64 v[8:9], v[4:5], 0, v[8:9]
	global_load_dwordx4 v[146:149], v[8:9], off
	s_waitcnt lgkmcnt(5)
	v_mfma_f32_32x32x16_bf16 v[34:49], v[230:233], v[208:211], v[34:49]
	ds_read_b128 v[230:233], v7 offset:0
	s_lshl_b32 s66, s65, 14
	s_mov_b32 s67, 0
	s_waitcnt lgkmcnt(5)
	v_mfma_f32_32x32x16_bf16 v[34:49], v[234:237], v[12:15], v[34:49]
	ds_read_b128 v[234:237], v7 offset:4608
	v_lshl_add_u64 v[10:11], v[164:165], 0, s[66:67]
	global_load_dwordx4 v[150:153], v[10:11], off
	s_waitcnt lgkmcnt(5)
	v_mfma_f32_32x32x16_bf16 v[18:33], v[214:217], v[200:203], v[18:33]
	ds_read_b128 v[214:217], v7 offset:32
	s_add_u32 s66, s66, 0x2000
	v_lshl_add_u64 v[10:11], v[164:165], 0, s[66:67]
	s_waitcnt lgkmcnt(5)
	v_mfma_f32_32x32x16_bf16 v[18:33], v[218:221], v[204:207], v[18:33]
	ds_read_b128 v[218:221], v7 offset:4640
	global_load_dwordx4 v[154:157], v[10:11], off

; #define MFMA(a, b, c) __builtin_amdgcn_mfma_f32_32x32x16_bf16((a), (b), (c), 0, 0, 0)
; DI void attn_scores(const unsigned char* kb, const bf16x8 (&qf)[4], int r, int h, f32x16& s0, f32x16& s1) {
; #pragma unroll
;     for (int i = 0; i < 16; ++i) { s0[i] = 0.f; s1[i] = 0.f; }
; #pragma unroll
;     for (int s = 0; s < 4; ++s) {
;         const bf16x8 k0 = *(const bf16x8*)(kb + r * KP + s * 32 + h * 16);
;         const bf16x8 k1 = *(const bf16x8*)(kb + (32 + r) * KP + s * 32 + h * 16);
;         s0 = MFMA(k0, qf[s], s0); s1 = MFMA(k1, qf[s], s1);
;     }
; }
; template <int DV>
; DI void attn_pv(const unsigned char* vb, const bf16x8 (&pf)[2][2], int r, int h, f32x16 (&o)[DV / 32]) {
; #pragma unroll
;     for (int dt = 0; dt < DV / 32; ++dt)
; #pragma unroll
;         for (int mt = 0; mt < 2; ++mt)
; #pragma unroll
;             for (int sp = 0; sp < 2; ++sp) {
;                 const bf16x8 vf = *(const bf16x8*)(vb + (dt * 32 + r) * VP + (2 * mt + sp) * 32 + h * 16);
;                 o[dt] = MFMA(vf, pf[mt][sp], o[dt]);
;             }
; }
	s_waitcnt lgkmcnt(5)
	v_mfma_f32_32x32x16_bf16 v[18:33], v[222:225], v[208:211], v[18:33]
	ds_read_b128 v[222:225], v7 offset:64
	s_waitcnt lgkmcnt(5)
	v_mfma_f32_32x32x16_bf16 v[18:33], v[226:229], v[12:15], v[18:33]
	ds_read_b128 v[226:229], v7 offset:4672
	s_waitcnt lgkmcnt(5)
	v_mfma_f32_32x32x16_bf16 v[114:129], v[230:233], v[130:133], 0
	ds_read_b128 v[230:233], v7 offset:96
	s_waitcnt lgkmcnt(5)
	v_mfma_f32_32x32x16_bf16 v[98:113], v[234:237], v[130:133], 0
	ds_read_b128 v[234:237], v7 offset:4704
	s_waitcnt lgkmcnt(5)
	v_mfma_f32_32x32x16_bf16 v[114:129], v[214:217], v[134:137], v[114:129]
	s_waitcnt lgkmcnt(4)
	v_mfma_f32_32x32x16_bf16 v[98:113], v[218:221], v[134:137], v[98:113]
	s_waitcnt lgkmcnt(3)
	v_mfma_f32_32x32x16_bf16 v[114:129], v[222:225], v[138:141], v[114:129]
	s_waitcnt lgkmcnt(2)
	v_mfma_f32_32x32x16_bf16 v[98:113], v[226:229], v[138:141], v[98:113]
	s_waitcnt lgkmcnt(1)
	v_mfma_f32_32x32x16_bf16 v[114:129], v[230:233], v[142:145], v[114:129]
	s_waitcnt lgkmcnt(0)
	v_mfma_f32_32x32x16_bf16 v[98:113], v[234:237], v[142:145], v[98:113]
	s_branch .Ldl_next
.Ldl_pvonly:
	ds_read_b128 v[214:217], v199 offset:9216
	ds_read_b128 v[218:221], v199 offset:9248
	ds_read_b128 v[222:225], v199 offset:9280
	ds_read_b128 v[226:229], v199 offset:9312
	ds_read_b128 v[230:233], v199 offset:13824
	ds_read_b128 v[234:237], v199 offset:13856
	s_waitcnt lgkmcnt(5)
	v_mfma_f32_32x32x16_bf16 v[66:81], v[214:217], v[200:203], v[66:81]
	ds_read_b128 v[214:217], v199 offset:13888
	s_waitcnt vmcnt(0)
	v_add3_u32 v10, s63, v159, v195
	s_waitcnt lgkmcnt(5)
	v_mfma_f32_32x32x16_bf16 v[66:81], v[218:221], v[204:207], v[66:81]
	ds_read_b128 v[218:221], v199 offset:13920
	ds_write_b128 v10, v[146:149]
	v_add3_u32 v10, s63, v196, v197
	s_waitcnt lgkmcnt(5)
	v_mfma_f32_32x32x16_bf16 v[66:81], v[222:225], v[208:211], v[66:81]
	ds_read_b128 v[222:225], v199 offset:18432
	v_add_u32_e32 v11, v10, v159
	v_add_u32_e32 v10, v10, v180
	s_waitcnt lgkmcnt(5)
	v_mfma_f32_32x32x16_bf16 v[66:81], v[226:229], v[12:15], v[66:81]
	ds_read_b128 v[226:229], v199 offset:18464
	v_add_u32_e32 v11, 0x2000, v11
	v_add_u32_e32 v10, 0x2000, v10
	s_waitcnt lgkmcnt(5)
	v_mfma_f32_32x32x16_bf16 v[50:65], v[230:233], v[200:203], v[50:65]
	ds_read_b128 v[230:233], v199 offset:18496
	ds_write2_b64 v11, v[150:151], v[152:153] offset0:128 offset1:130
	ds_write2_b64 v10, v[154:155], v[156:157] offset0:128 offset1:130
	s_waitcnt lgkmcnt(5)
	v_mfma_f32_32x32x16_bf16 v[50:65], v[234:237], v[204:207], v[50:65]
	ds_read_b128 v[234:237], v199 offset:18528

; #define MFMA(a, b, c) __builtin_amdgcn_mfma_f32_32x32x16_bf16((a), (b), (c), 0, 0, 0)
; template <int DV, bool HAS_V>
; DI void kv_gload(KVStage<DV>& st, const bf16_t* __restrict__ Kb, const bf16_t* __restrict__ VTb, int ldv, int key0) {
;     const int tid = threadIdx.x;
;     st.k[0] = *(const u32x4*)(Kb + (size_t)(key0 + (tid >> 3)) * 64 + (tid & 7) * 8);
;     if (HAS_V) {
; #pragma unroll
;         for (int i = 0; i < DV / 64; ++i) { const int c = tid + 512 * i; st.v[i] = *(const u32x4*)(VTb + (size_t)(key0 >> 6) * (DV * 64) + c * 8); }
;     }
; }
; template <int DV>
; DI void attn_pv(const unsigned char* vb, const bf16x8 (&pf)[2][2], int r, int h, f32x16 (&o)[DV / 32]) {
; #pragma unroll
;     for (int dt = 0; dt < DV / 32; ++dt)
; #pragma unroll
;         for (int mt = 0; mt < 2; ++mt)
; #pragma unroll
;             for (int sp = 0; sp < 2; ++sp) {
;                 const bf16x8 vf = *(const bf16x8*)(vb + (dt * 32 + r) * VP + (2 * mt + sp) * 32 + h * 16);
;                 o[dt] = MFMA(vf, pf[mt][sp], o[dt]);
;             }
; }
	s_add_i32 s65, s24, 3
	s_waitcnt lgkmcnt(5)
	v_mfma_f32_32x32x16_bf16 v[50:65], v[214:217], v[208:211], v[50:65]
	ds_read_b128 v[214:217], v199 offset:23040
	s_add_i32 s66, s58, -1
	s_min_u32 s65, s65, s66
	s_waitcnt lgkmcnt(5)
	v_mfma_f32_32x32x16_bf16 v[50:65], v[218:221], v[12:15], v[50:65]
	ds_read_b128 v[218:221], v199 offset:23072
	s_lshl_b32 s66, s65, 6
	v_add_u32_e32 v8, s66, v187
	s_waitcnt lgkmcnt(5)
	v_mfma_f32_32x32x16_bf16 v[34:49], v[222:225], v[200:203], v[34:49]
	ds_read_b128 v[222:225], v199 offset:23104
	v_mov_b32_e32 v9, v3
	v_lshlrev_b64 v[8:9], 7, v[8:9]
	s_waitcnt lgkmcnt(5)
	v_mfma_f32_32x32x16_bf16 v[34:49], v[226:229], v[204:207], v[34:49]
	ds_read_b128 v[226:229], v199 offset:23136
	v_lshl_add_u64 v[8:9], v[4:5], 0, v[8:9]
	global_load_dwordx4 v[146:149], v[8:9], off
	s_waitcnt lgkmcnt(5)
	v_mfma_f32_32x32x16_bf16 v[34:49], v[230:233], v[208:211], v[34:49]
	s_lshl_b32 s66, s65, 14
	s_mov_b32 s67, 0
	s_waitcnt lgkmcnt(4)
	v_mfma_f32_32x32x16_bf16 v[34:49], v[234:237], v[12:15], v[34:49]
	v_lshl_add_u64 v[10:11], v[164:165], 0, s[66:67]
	global_load_dwordx4 v[150:153], v[10:11], off
	s_waitcnt lgkmcnt(3)
	v_mfma_f32_32x32x16_bf16 v[18:33], v[214:217], v[200:203], v[18:33]
	s_add_u32 s66, s66, 0x2000
	v_lshl_add_u64 v[10:11], v[164:165], 0, s[66:67]
	s_waitcnt lgkmcnt(2)
	v_mfma_f32_32x32x16_bf16 v[18:33], v[218:221], v[204:207], v[18:33]
	global_load_dwordx4 v[154:157], v[10:11], off

; #define MFMA(a, b, c) __builtin_amdgcn_mfma_f32_32x32x16_bf16((a), (b), (c), 0, 0, 0)
; template <int DV>
; DI void attn_pv(const unsigned char* vb, const bf16x8 (&pf)[2][2], int r, int h, f32x16 (&o)[DV / 32]) {
; #pragma unroll
;     for (int dt = 0; dt < DV / 32; ++dt)
; #pragma unroll
;         for (int mt = 0; mt < 2; ++mt)
; #pragma unroll
;             for (int sp = 0; sp < 2; ++sp) {
;                 const bf16x8 vf = *(const bf16x8*)(vb + (dt * 32 + r) * VP + (2 * mt + sp) * 32 + h * 16);
;                 o[dt] = MFMA(vf, pf[mt][sp], o[dt]);
;             }
; }
	s_waitcnt lgkmcnt(1)
	v_mfma_f32_32x32x16_bf16 v[18:33], v[222:225], v[208:211], v[18:33]
	s_waitcnt lgkmcnt(0)
	v_mfma_f32_32x32x16_bf16 v[18:33], v[226:229], v[12:15], v[18:33]
	s_branch .Ldl_next
